# mlp-norm rows streamed by LDS-DMA into a per-wave 3-row LDS ring instead of register loads
# baseline (speedup 1.0000x reference)
; __device__ __forceinline__ int opaque_tid() { int t = threadIdx.x; asm volatile("" : "+v"(t)); return t; }
; __device__ __forceinline__ unsigned pk_bf16(float lo, float hi) { f32x2_t v = {lo, hi}; bf16x2_t b = __builtin_convertvector(v, bf16x2_t); return __builtin_bit_cast(unsigned, b); }
; __device__ __forceinline__ void norm_phase(const float* src_real, const float* src_meta, const float* w, bf16_t* hn, int G) {
;     const int tid = opaque_tid(), lane = tid & 63, wid = __builtin_amdgcn_readfirstlane(tid >> 6);
;     const int gw = blockIdx.x * NWAVES + wid, NGW = G * NWAVES;
;     f32x4 wv[4];
; #pragma unroll
;     for (int j = 0; j < 4; ++j) wv[j] = ((const f32x4*)w)[lane + 64 * j];
;     for (int row = gw; row < MT; row += NGW) {
;         const float* xr = row < MR ? src_real + (size_t)row * DM : src_meta + (size_t)(row - MR) * DM;
;         f32x4 v[4]; float s = 0.f;
; #pragma unroll
;         for (int j = 0; j < 4; ++j) { v[j] = ((const f32x4*)xr)[lane + 64 * j]; s += (v[j].x * v[j].x + v[j].y * v[j].y) + (v[j].z * v[j].z + v[j].w * v[j].w); }
;         const float r = rsqrtf(wave_sum(s) * (1.f / DM) + EPS);
;         u32x2* o8 = (u32x2*)(hn + (size_t)row * DM) + lane;
; #pragma unroll
;         for (int j = 0; j < 4; ++j) { u32x2 o; o.x = pk_bf16(v[j].x * r * wv[j].x, v[j].y * r * wv[j].y); o.y = pk_bf16(v[j].z * r * wv[j].z, v[j].w * r * wv[j].w); o8[64 * j] = o; }
;     }
.LBB0_915:
	s_mov_b64 s[14:15], s[90:91]
	v_mov_b32_e32 v0, v194
	v_readlane_b32 s3, v253, 4
	v_readfirstlane_b32 s2, v0
	s_ashr_i32 s2, s2, 6
	s_add_i32 s12, s2, s3
	s_cmp_gt_i32 s12, 0x800f
	s_cbranch_scc1 .LBB0_920
	s_load_dwordx4 s[8:11], s[14:15], 0x80
	s_load_dwordx2 s[4:5], s[14:15], 0x60
	v_readlane_b32 s14, v254, 62
	v_readlane_b32 s15, v254, 63
	v_and_b32_e32 v28, 63, v0
	s_waitcnt lgkmcnt(0)
	s_add_u32 s2, s10, 0x6300000
	s_addc_u32 s3, s11, 0
	s_lshl_b64 s[14:15], s[14:15], 2
	s_add_u32 s4, s4, s14
	v_lshlrev_b32_e32 v0, 4, v28
	s_addc_u32 s5, s5, s15
	global_load_dwordx4 v[2:5], v0, s[4:5] offset:3072
	global_load_dwordx4 v[6:9], v0, s[4:5] offset:2048
	global_load_dwordx4 v[10:13], v0, s[4:5] offset:1024
	global_load_dwordx4 v[18:21], v0, s[4:5]
	v_cmp_lt_i32_e32 vcc, v207, v201
	s_mov_b64 s[4:5], 0x6400000
	s_ashr_i32 s13, s12, 31
	v_cndmask_b32_e32 v0, v200, v207, vcc
	v_cmp_lt_i32_e32 vcc, v206, v201
	v_lshlrev_b32_e32 v17, 2, v0
	s_nop 0
	v_cndmask_b32_e32 v0, v200, v206, vcc
	v_lshlrev_b32_e32 v22, 2, v0
	v_xor_b32_e32 v0, 4, v200
	v_cmp_lt_i32_e32 vcc, v0, v201
	s_nop 1
	v_cndmask_b32_e32 v0, v200, v0, vcc
	v_lshlrev_b32_e32 v23, 2, v0
	v_xor_b32_e32 v0, 8, v200
	v_cmp_lt_i32_e32 vcc, v0, v201
	s_nop 1
	v_cndmask_b32_e32 v0, v200, v0, vcc
	v_lshlrev_b32_e32 v24, 2, v0
	v_xor_b32_e32 v0, 16, v200
	v_cmp_lt_i32_e32 vcc, v0, v201
	s_nop 1
	v_cndmask_b32_e32 v0, v200, v0, vcc
	v_lshlrev_b32_e32 v25, 2, v0
	v_xor_b32_e32 v0, 32, v200
	v_cmp_lt_i32_e32 vcc, v0, v201
	s_nop 1
	v_cndmask_b32_e32 v0, v200, v0, vcc
	s_waitcnt vmcnt(6)
	v_lshlrev_b32_e32 v26, 2, v0
	v_lshlrev_b32_e32 v0, 3, v28
	v_lshl_add_u64 v[14:15], s[10:11], 0, v[0:1]
	v_lshl_add_u64 v[14:15], v[14:15], 0, s[4:5]
	s_lshl_b64 s[4:5], s[12:13], 12
	s_add_u32 s8, s8, s4
	s_addc_u32 s9, s9, s5
	v_lshlrev_b32_e32 v0, 4, v28
	v_readlane_b32 s16, v254, 10
	v_readlane_b32 s17, v254, 11
	v_readfirstlane_b32 s34, v194
	s_mov_b32 s30, 0x800000
	s_mov_b32 s31, 1
	s_lshr_b32 s34, s34, 6
	s_lshl_b32 s34, s34, 14
	s_mov_b64 s[10:11], s[12:13]
	s_mov_b32 s32, s34
	s_mov_b32 s33, s34
	s_add_i32 s4, s12, 0xffff8000
	s_mov_b32 s5, 0
	s_lshl_b64 s[4:5], s[4:5], 12
	s_add_u32 s4, s2, s4
	s_addc_u32 s5, s3, s5
	s_cmp_lt_i32 s12, 0x8000
	s_cselect_b64 s[14:15], s[8:9], s[4:5]
	s_mov_b32 m0, s32
	s_nop 0
	global_load_lds_dwordx4 v0, s[14:15]
	global_load_lds_dwordx4 v0, s[14:15] offset:1024
	global_load_lds_dwordx4 v0, s[14:15] offset:2048
	global_load_lds_dwordx4 v0, s[14:15] offset:3072
	s_add_u32 s12, s12, s88
	s_addc_u32 s13, s13, s89
	s_add_u32 s8, s8, s16
	s_addc_u32 s9, s9, s17
	s_add_i32 s32, s32, 0x1000
	s_sub_i32 s4, s32, s34
	s_cmp_eq_u32 s4, 0x3000
	s_cselect_b32 s32, s34, s32
	s_add_i32 s4, s12, 0xffff8000
	s_mov_b32 s5, 0
	s_lshl_b64 s[4:5], s[4:5], 12
	s_add_u32 s4, s2, s4
	s_addc_u32 s5, s3, s5
	s_cmp_lt_i32 s12, 0x8000
	s_cselect_b64 s[14:15], s[8:9], s[4:5]
	s_mov_b32 m0, s32
	s_nop 0
	global_load_lds_dwordx4 v0, s[14:15]
	global_load_lds_dwordx4 v0, s[14:15] offset:1024
	global_load_lds_dwordx4 v0, s[14:15] offset:2048
	global_load_lds_dwordx4 v0, s[14:15] offset:3072
	s_add_u32 s12, s12, s88
	s_addc_u32 s13, s13, s89
	s_add_u32 s8, s8, s16
	s_addc_u32 s9, s9, s17
	s_add_i32 s32, s32, 0x1000
	s_sub_i32 s4, s32, s34
	s_cmp_eq_u32 s4, 0x3000
	s_cselect_b32 s32, s34, s32
; __device__ __forceinline__ unsigned pk_bf16(float lo, float hi) { f32x2_t v = {lo, hi}; bf16x2_t b = __builtin_convertvector(v, bf16x2_t); return __builtin_bit_cast(unsigned, b); }
; __device__ __forceinline__ void norm_phase(const float* src_real, const float* src_meta, const float* w, bf16_t* hn, int G) {
;     ...
;     for (int row = gw; row < MT; row += NGW) {
;         const float* xr = row < MR ? src_real + (size_t)row * DM : src_meta + (size_t)(row - MR) * DM;
;         f32x4 v[4]; float s = 0.f;
; #pragma unroll
;         for (int j = 0; j < 4; ++j) { v[j] = ((const f32x4*)xr)[lane + 64 * j]; s += (v[j].x * v[j].x + v[j].y * v[j].y) + (v[j].z * v[j].z + v[j].w * v[j].w); }
;         const float r = rsqrtf(wave_sum(s) * (1.f / DM) + EPS);
;         u32x2* o8 = (u32x2*)(hn + (size_t)row * DM) + lane;
; #pragma unroll
;         for (int j = 0; j < 4; ++j) { u32x2 o; o.x = pk_bf16(v[j].x * r * wv[j].x, v[j].y * r * wv[j].y); o.y = pk_bf16(v[j].z * r * wv[j].z, v[j].w * r * wv[j].w); o8[64 * j] = o; }
;     }
.Lmlpnorm_loop:
	s_cmp_lt_i32 s12, 0x8010
	s_cbranch_scc0 .Lmlpnorm_noissue
	s_add_i32 s4, s12, 0xffff8000
	s_mov_b32 s5, 0
	s_lshl_b64 s[4:5], s[4:5], 12
	s_add_u32 s4, s2, s4
	s_addc_u32 s5, s3, s5
	s_cmp_lt_i32 s12, 0x8000
	s_cselect_b64 s[14:15], s[8:9], s[4:5]
	s_mov_b32 m0, s32
	s_nop 0
	global_load_lds_dwordx4 v0, s[14:15]
	global_load_lds_dwordx4 v0, s[14:15] offset:1024
	global_load_lds_dwordx4 v0, s[14:15] offset:2048
	global_load_lds_dwordx4 v0, s[14:15] offset:3072
	s_add_u32 s12, s12, s88
	s_addc_u32 s13, s13, s89
	s_add_u32 s8, s8, s16
	s_addc_u32 s9, s9, s17
	s_add_i32 s32, s32, 0x1000
	s_sub_i32 s4, s32, s34
	s_cmp_eq_u32 s4, 0x3000
	s_cselect_b32 s32, s34, s32
	s_cmp_lg_u32 s31, 0
	s_cbranch_scc1 .Lmlpnorm_noissue
	s_waitcnt vmcnt(12)
	s_branch .Lmlpnorm_have
.Lmlpnorm_noissue:
	s_waitcnt vmcnt(8)
.Lmlpnorm_have:
	s_mov_b32 s31, 0
	v_add_u32_e32 v74, s33, v0
	ds_read_b128 v[28:31], v74
	ds_read_b128 v[32:35], v74 offset:1024
	ds_read_b128 v[36:39], v74 offset:2048
	ds_read_b128 v[40:43], v74 offset:3072
	s_waitcnt lgkmcnt(0)
	v_mul_f32_e32 v70, v28, v28
	v_mul_f32_e32 v71, v32, v32
	v_mul_f32_e32 v72, v36, v36
	v_mul_f32_e32 v73, v40, v40
	v_fmac_f32_e32 v70, v29, v29
	v_fmac_f32_e32 v71, v33, v33
	v_fmac_f32_e32 v72, v37, v37
	v_fmac_f32_e32 v73, v41, v41
	v_fmac_f32_e32 v70, v30, v30
	v_fmac_f32_e32 v71, v34, v34
	v_fmac_f32_e32 v72, v38, v38
	v_fmac_f32_e32 v73, v42, v42
	v_fmac_f32_e32 v70, v31, v31
	v_fmac_f32_e32 v71, v35, v35
	v_fmac_f32_e32 v72, v39, v39
	v_fmac_f32_e32 v73, v43, v43
	v_add_f32_e32 v70, v70, v71
	v_add_f32_e32 v72, v72, v73
	s_lshl_b64 s[4:5], s[10:11], 11
	v_add_f32_e32 v27, v70, v72
	ds_bpermute_b32 v44, v17, v27
	s_waitcnt lgkmcnt(0)
	v_add_f32_e32 v27, v27, v44
	ds_bpermute_b32 v44, v22, v27
	s_waitcnt lgkmcnt(0)
	v_add_f32_e32 v27, v27, v44
	ds_bpermute_b32 v44, v23, v27
	s_waitcnt lgkmcnt(0)
	v_add_f32_e32 v27, v27, v44
	ds_bpermute_b32 v44, v24, v27
	s_waitcnt lgkmcnt(0)
	v_add_f32_e32 v27, v27, v44
	ds_bpermute_b32 v44, v25, v27
	s_waitcnt lgkmcnt(0)
	v_add_f32_e32 v27, v27, v44
	ds_bpermute_b32 v44, v26, v27
	s_waitcnt lgkmcnt(0)
	v_add_f32_e32 v27, v27, v44
	v_fmamk_f32 v27, v27, 0x3a800000, v195
	v_cmp_gt_f32_e32 vcc, s30, v27
	v_mul_f32_e32 v44, 0x4b800000, v27
	v_lshl_add_u64 v[46:47], v[14:15], 0, s[4:5]
	s_nop 0
	v_cndmask_b32_e32 v27, v27, v44, vcc
	v_rsq_f32_e32 v27, v27
	s_nop 0
	v_mul_f32_e32 v44, 0x45800000, v27
	v_cndmask_b32_e32 v44, v27, v44, vcc
	v_pk_mul_f32 v[28:29], v[28:29], v[44:45] op_sel_hi:[1,0]
	v_pk_mul_f32 v[30:31], v[30:31], v[44:45] op_sel_hi:[1,0]
	v_pk_mul_f32 v[32:33], v[32:33], v[44:45] op_sel_hi:[1,0]
	v_pk_mul_f32 v[34:35], v[34:35], v[44:45] op_sel_hi:[1,0]
	v_pk_mul_f32 v[36:37], v[36:37], v[44:45] op_sel_hi:[1,0]
	v_pk_mul_f32 v[38:39], v[38:39], v[44:45] op_sel_hi:[1,0]
	v_pk_mul_f32 v[40:41], v[40:41], v[44:45] op_sel_hi:[1,0]
	v_pk_mul_f32 v[42:43], v[42:43], v[44:45] op_sel_hi:[1,0]
	v_pk_mul_f32 v[28:29], v[18:19], v[28:29]
	v_pk_mul_f32 v[30:31], v[20:21], v[30:31]
	v_pk_mul_f32 v[32:33], v[10:11], v[32:33]
	v_pk_mul_f32 v[34:35], v[12:13], v[34:35]
	v_pk_mul_f32 v[36:37], v[6:7], v[36:37]
	v_pk_mul_f32 v[38:39], v[8:9], v[38:39]
	v_pk_mul_f32 v[40:41], v[2:3], v[40:41]
	v_pk_mul_f32 v[42:43], v[4:5], v[42:43]
	v_cvt_pk_bf16_f32 v28, v28, v29
	v_cvt_pk_bf16_f32 v29, v30, v31
	v_cvt_pk_bf16_f32 v32, v32, v33
	v_cvt_pk_bf16_f32 v33, v34, v35
	v_cvt_pk_bf16_f32 v36, v36, v37
	v_cvt_pk_bf16_f32 v37, v38, v39
	v_cvt_pk_bf16_f32 v40, v40, v41
	v_cvt_pk_bf16_f32 v41, v42, v43
	global_store_dwordx2 v[46:47], v[28:29], off
	global_store_dwordx2 v[46:47], v[32:33], off offset:512
	global_store_dwordx2 v[46:47], v[36:37], off offset:1024
	global_store_dwordx2 v[46:47], v[40:41], off offset:1536
	s_add_u32 s10, s10, s88
	s_addc_u32 s11, s11, s89
	s_add_i32 s33, s33, 0x1000
	s_sub_i32 s4, s33, s34
	s_cmp_eq_u32 s4, 0x3000
	s_cselect_b32 s33, s34, s33
	s_cmp_lt_i32 s10, 0x8010
	s_cbranch_scc1 .Lmlpnorm_loop
